# mix2 item: LDS fragment reads hoisted 3 waits ahead into free VGPRs with counted lgkmcnt waits (hazard slots kept), on v21
# baseline (speedup 1.0000x reference)
.LBB0_412:
	ds_read_b128 v[196:199], v161
	ds_read_b128 v[200:203], v161 offset:64
	ds_read_b128 v[204:207], v161 offset:4416
	ds_read_b128 v[208:211], v161 offset:13120
	ds_read_b128 v[212:215], v161 offset:128
	ds_read_b128 v[216:219], v161 offset:192
	s_ashr_i32 s25, s24, 7
	s_add_i32 s26, s24, 0xfffffc00
	s_cmpk_gt_i32 s24, 0x3ff
	s_cselect_b64 vcc, -1, 0
	s_and_b64 s[20:21], vcc, exec
	s_cselect_b32 s25, s26, s25
	s_and_b32 s24, s25, 3
	v_cvt_f32_ubyte0_e32 v1, s24
	v_sub_f32_e32 v1, 0xc0a00000, v1
	s_mov_b32 s20, 0xc2fc0000
	v_cmp_gt_f32_e64 s[44:45], s20, v1
	s_and_b64 s[20:21], s[44:45], exec
	s_cselect_b32 s20, 0xffffffc0, 0
	v_cndmask_b32_e64 v2, 0, v189, s[44:45]
	v_add_f32_e32 v1, v1, v2
	v_exp_f32_e32 v1, v1
	s_lshl_b32 s24, s24, 7
	v_add_u32_e32 v2, s24, v129
	v_ashrrev_i32_e32 v3, 31, v2
	v_ldexp_f32 v1, v1, s20
	v_sub_f32_e32 v86, 1.0, v1
	v_lshl_add_u64 v[84:85], v[2:3], 2, s[12:13]
	global_load_dword v113, v[84:85], off
	global_load_dword v3, v[84:85], off offset:64
	global_load_dword v2, v[84:85], off offset:128
	global_load_dword v1, v[84:85], off offset:192
	v_log_f32_e32 v88, v86
	s_nop 0
	s_nop 0
	ds_read_b128 v[224:227], v161 offset:4352
	s_waitcnt lgkmcnt(5)
	v_mfma_f32_16x16x32_bf16 v[84:87], v[196:199], v[76:79], 0
	s_nop 0
	v_mul_f32_e32 v89, v88, v130
	s_nop 0
	v_mfma_f32_16x16x32_bf16 v[84:87], v[200:203], v[68:71], v[84:87]
	s_nop 0
	ds_read_b128 v[196:199], v161 offset:4480
	s_waitcnt lgkmcnt(3)
	v_mfma_f32_16x16x32_bf16 v[84:87], v[212:215], v[80:83], v[84:87]
	s_nop 0
	ds_read_b128 v[200:203], v161 offset:4544
	s_waitcnt lgkmcnt(3)
	v_mfma_f32_16x16x32_bf16 v[84:87], v[216:219], v[72:75], v[84:87]
	v_exp_f32_e32 v90, v89
	v_mul_f32_e32 v89, v88, v131
	v_exp_f32_e32 v91, v89
	v_mul_f32_e32 v89, v88, v132
	s_nop 3
	v_pk_mul_f32 v[84:85], v[90:91], v[84:85]
	v_exp_f32_e32 v90, v89
	v_mul_f32_e32 v89, v88, v133
	v_exp_f32_e32 v91, v89
	v_cvt_pk_bf16_f32 v84, v84, v85
	v_mul_f32_e32 v89, v88, v136
	v_pk_mul_f32 v[86:87], v[90:91], v[86:87]
	s_nop 0
	ds_read_b128 v[212:215], v161 offset:8768
	ds_read_b128 v[216:219], v161 offset:8704
	s_waitcnt lgkmcnt(4)
	v_mfma_f32_16x16x32_bf16 v[90:93], v[224:227], v[76:79], 0
	v_cvt_pk_bf16_f32 v85, v86, v87
	v_mul_f32_e32 v86, v88, v134
	v_mul_f32_e32 v87, v88, v135
	v_mfma_f32_16x16x32_bf16 v[90:93], v[204:207], v[68:71], v[90:93]
	s_nop 0
	v_exp_f32_e32 v86, v86
	v_exp_f32_e32 v87, v87
	ds_read_b128 v[204:207], v161 offset:8832
	s_waitcnt lgkmcnt(4)
	v_mfma_f32_16x16x32_bf16 v[90:93], v[196:199], v[80:83], v[90:93]
	s_nop 0
	ds_read_b128 v[196:199], v161 offset:8896
	s_waitcnt lgkmcnt(4)
	v_mfma_f32_16x16x32_bf16 v[90:93], v[200:203], v[72:75], v[90:93]
	s_nop 0
	s_nop 6
	v_pk_mul_f32 v[86:87], v[86:87], v[90:91]
	v_exp_f32_e32 v90, v89
	v_mul_f32_e32 v89, v88, v137
	v_exp_f32_e32 v91, v89
	v_cvt_pk_bf16_f32 v86, v86, v87
	v_mul_f32_e32 v89, v88, v138
	v_pk_mul_f32 v[90:91], v[90:91], v[92:93]
	s_nop 0
	v_cvt_pk_bf16_f32 v87, v90, v91
	s_nop 0
	ds_read_b128 v[200:203], v161 offset:13056
	s_waitcnt lgkmcnt(3)
	v_mfma_f32_16x16x32_bf16 v[90:93], v[216:219], v[76:79], 0
	v_mfma_f32_16x16x32_bf16 v[90:93], v[212:215], v[68:71], v[90:93]
	s_nop 0
	ds_read_b128 v[212:215], v161 offset:13184
	s_waitcnt lgkmcnt(3)
	v_mfma_f32_16x16x32_bf16 v[90:93], v[204:207], v[80:83], v[90:93]
	s_nop 0
	ds_read_b128 v[204:207], v161 offset:13248
	s_waitcnt lgkmcnt(3)
	v_mfma_f32_16x16x32_bf16 v[90:93], v[196:199], v[72:75], v[90:93]
	v_exp_f32_e32 v94, v89
	v_mul_f32_e32 v89, v88, v139
	v_exp_f32_e32 v95, v89
	v_mul_f32_e32 v89, v88, v140
	s_nop 3
	v_pk_mul_f32 v[90:91], v[94:95], v[90:91]
	v_exp_f32_e32 v94, v89
	v_mul_f32_e32 v89, v88, v141
	v_exp_f32_e32 v95, v89
	v_cvt_pk_bf16_f32 v96, v90, v91
	v_mul_f32_e32 v89, v88, v142
	v_pk_mul_f32 v[92:93], v[94:95], v[92:93]
	s_nop 0
	v_cvt_pk_bf16_f32 v97, v92, v93
	s_nop 0
	ds_read_b128 v[196:199], v162 offset:34880
	ds_read_b128 v[216:219], v162 offset:34816
	s_waitcnt lgkmcnt(4)
	v_mfma_f32_16x16x32_bf16 v[90:93], v[200:203], v[76:79], 0
	v_exp_f32_e32 v94, v89
	v_mul_f32_e32 v89, v88, v143
	v_exp_f32_e32 v95, v89
	v_mfma_f32_16x16x32_bf16 v[90:93], v[208:211], v[68:71], v[90:93]
	s_nop 0
	v_mul_f32_e32 v89, v88, v144
	ds_read_b128 v[200:203], v162 offset:34944
	s_waitcnt lgkmcnt(4)
	v_mfma_f32_16x16x32_bf16 v[90:93], v[212:215], v[80:83], v[90:93]
	s_nop 0
	ds_read_b128 v[208:211], v162 offset:35008
	s_waitcnt lgkmcnt(4)
	v_mfma_f32_16x16x32_bf16 v[90:93], v[204:207], v[72:75], v[90:93]
	s_nop 0
	s_nop 6
	v_pk_mul_f32 v[90:91], v[94:95], v[90:91]
	v_exp_f32_e32 v94, v89
	v_mul_f32_e32 v89, v88, v145
	v_exp_f32_e32 v95, v89
	v_cvt_pk_bf16_f32 v98, v90, v91
	v_mul_f32_e32 v89, v88, v146
	v_exp_f32_e32 v176, v89
	v_pk_mul_f32 v[92:93], v[94:95], v[92:93]
	v_mul_f32_e32 v89, v88, v147
	v_cvt_pk_bf16_f32 v99, v92, v93
	s_nop 0
	ds_read_b64_tr_b16 v[204:205], v163 offset:17408
	ds_read_b64_tr_b16 v[206:207], v163 offset:21760
	s_waitcnt lgkmcnt(4)
	v_mfma_f32_16x16x32_bf16 v[90:93], v[76:79], v[216:219], 0
	v_exp_f32_e32 v177, v89
	v_mul_f32_e32 v89, v88, v148
	v_mul_f32_e32 v88, v88, v149
	v_mfma_f32_16x16x32_bf16 v[90:93], v[68:71], v[196:199], v[90:93]
	s_nop 0
	v_exp_f32_e32 v178, v89
	v_exp_f32_e32 v179, v88
	ds_read_b64_tr_b16 v[196:197], v163 offset:26112
	ds_read_b64_tr_b16 v[198:199], v163 offset:30464
	ds_read_b128 v[212:215], v164 offset:34880
	s_waitcnt lgkmcnt(6)
	v_mfma_f32_16x16x32_bf16 v[90:93], v[80:83], v[200:203], v[90:93]
	s_nop 0
	ds_read_b128 v[200:203], v164 offset:34816
	s_waitcnt lgkmcnt(6)
	v_mfma_f32_16x16x32_bf16 v[90:93], v[72:75], v[208:211], v[90:93]
	s_nop 0
	s_nop 0
	s_nop 5
	v_pk_mul_f32 v[92:93], v[178:179], v[92:93]
	v_pk_mul_f32 v[90:91], v[176:177], v[90:91]
	ds_read_b128 v[208:211], v164 offset:34944
	s_waitcnt lgkmcnt(5)
	s_nop 0
	v_mfma_f32_16x16x32_bf16 v[88:91], v[84:87], v[204:207], v[90:93]
	s_nop 2
	s_nop 0
	s_nop 0
	s_nop 0
	ds_read_b128 v[204:207], v164 offset:35008
	s_waitcnt lgkmcnt(3)
	v_mfma_f32_16x16x32_bf16 v[88:91], v[96:99], v[196:199], v[88:91]
	s_nop 0
	ds_read_b64_tr_b16 v[196:197], v165 offset:17408
	ds_read_b64_tr_b16 v[198:199], v165 offset:21760
	s_waitcnt lgkmcnt(4)
	v_mfma_f32_16x16x32_bf16 v[92:95], v[76:79], v[200:203], 0
	v_mfma_f32_16x16x32_bf16 v[92:95], v[68:71], v[212:215], v[92:95]
	s_nop 0
	ds_read_b64_tr_b16 v[200:201], v165 offset:26112
	ds_read_b64_tr_b16 v[202:203], v165 offset:30464
	ds_read_b128 v[212:215], v166 offset:34880
	s_waitcnt lgkmcnt(6)
	v_mfma_f32_16x16x32_bf16 v[92:95], v[80:83], v[208:211], v[92:95]
	s_nop 0
	ds_read_b128 v[208:211], v166 offset:34816
	s_waitcnt lgkmcnt(6)
	v_mfma_f32_16x16x32_bf16 v[92:95], v[72:75], v[204:207], v[92:95]
	s_nop 0
	s_nop 0
	s_nop 5
	v_pk_mul_f32 v[94:95], v[178:179], v[94:95]
	v_pk_mul_f32 v[92:93], v[176:177], v[92:93]
	ds_read_b128 v[204:207], v166 offset:34944
	s_waitcnt lgkmcnt(5)
	s_nop 0
	v_mfma_f32_16x16x32_bf16 v[92:95], v[84:87], v[196:199], v[92:95]
	s_nop 0
	s_nop 0
	s_nop 0
	ds_read_b128 v[196:199], v166 offset:35008
	s_waitcnt lgkmcnt(3)
	v_mfma_f32_16x16x32_bf16 v[92:95], v[96:99], v[200:203], v[92:95]
	s_nop 0
	ds_read_b64_tr_b16 v[200:201], v167 offset:17408
	ds_read_b64_tr_b16 v[202:203], v167 offset:21760
	s_waitcnt lgkmcnt(4)
	v_mfma_f32_16x16x32_bf16 v[100:103], v[76:79], v[208:211], 0
	v_mfma_f32_16x16x32_bf16 v[100:103], v[68:71], v[212:215], v[100:103]
	s_nop 0
	ds_read_b64_tr_b16 v[208:209], v167 offset:26112
	ds_read_b64_tr_b16 v[210:211], v167 offset:30464
	s_waitcnt lgkmcnt(5)
	v_mfma_f32_16x16x32_bf16 v[100:103], v[80:83], v[204:207], v[100:103]
	s_nop 0
	ds_read_b128 v[204:207], v168 offset:34816
	s_waitcnt lgkmcnt(5)
	v_mfma_f32_16x16x32_bf16 v[100:103], v[72:75], v[196:199], v[100:103]
	s_nop 0
	s_nop 0
	s_nop 5
	v_pk_mul_f32 v[102:103], v[178:179], v[102:103]
	v_pk_mul_f32 v[100:101], v[176:177], v[100:101]
	s_waitcnt lgkmcnt(3)
	s_nop 0
	v_mfma_f32_16x16x32_bf16 v[100:103], v[84:87], v[200:203], v[100:103]
	s_nop 0
	s_nop 0
	ds_read_b128 v[196:199], v168 offset:34944
	s_waitcnt lgkmcnt(2)
	v_mfma_f32_16x16x32_bf16 v[100:103], v[96:99], v[208:211], v[100:103]
	s_nop 0
	ds_read_b128 v[200:203], v168 offset:35008
	s_waitcnt lgkmcnt(2)
	v_mfma_f32_16x16x32_bf16 v[76:79], v[76:79], v[204:207], 0
	ds_read_b128 v[172:175], v168 offset:34880
	ds_read_b64_tr_b16 v[204:205], v169 offset:17408
	ds_read_b64_tr_b16 v[206:207], v169 offset:21760
	s_waitcnt lgkmcnt(2)
	v_mfma_f32_16x16x32_bf16 v[68:71], v[68:71], v[172:175], v[76:79]
	s_nop 4
	s_nop 0
	ds_read_b64_tr_b16 v[208:209], v169 offset:26112
	ds_read_b64_tr_b16 v[210:211], v169 offset:30464
	s_waitcnt lgkmcnt(4)
	v_mfma_f32_16x16x32_bf16 v[68:71], v[80:83], v[196:199], v[68:71]
	s_nop 0
	s_waitcnt lgkmcnt(4)
	v_mfma_f32_16x16x32_bf16 v[68:71], v[72:75], v[200:203], v[68:71]
	s_nop 0
	s_nop 0
	v_mul_f32_e32 v77, v100, v100
	v_mov_b32_e32 v76, v100
	s_nop 3
	v_pk_mul_f32 v[70:71], v[178:179], v[70:71]
	v_pk_mul_f32 v[68:69], v[176:177], v[68:69]
	s_waitcnt lgkmcnt(2)
	s_nop 0
	v_mfma_f32_16x16x32_bf16 v[68:71], v[84:87], v[204:207], v[68:71]
	s_nop 0
	s_nop 0
	s_waitcnt lgkmcnt(0)
	v_mfma_f32_16x16x32_bf16 v[68:71], v[96:99], v[208:211], v[68:71]
	v_add_f32_e32 v72, 0, v88
	v_mul_f32_e32 v73, v88, v88
	v_mul_f32_e32 v75, v92, v92
	v_mov_b32_e32 v74, v92
	v_pk_add_f32 v[72:73], v[72:73], v[74:75]
	s_nop 2
	v_mul_f32_e32 v79, v68, v68
	v_pk_add_f32 v[72:73], v[72:73], v[76:77]
	v_mov_b32_e32 v78, v68
	v_pk_add_f32 v[72:73], v[72:73], v[78:79]
	ds_bpermute_b32 v74, v150, v72
	ds_bpermute_b32 v75, v150, v73
	v_mul_f32_e32 v77, v93, v93
	v_mov_b32_e32 v76, v93
	v_mul_f32_e32 v79, v101, v101
	v_mov_b32_e32 v78, v101
	s_waitcnt lgkmcnt(0)
	v_pk_add_f32 v[72:73], v[72:73], v[74:75]
	ds_bpermute_b32 v74, v151, v72
	ds_bpermute_b32 v75, v151, v73
	v_mul_f32_e32 v81, v69, v69
	v_mov_b32_e32 v80, v69
	v_mul_f32_e32 v83, v70, v70
	v_mov_b32_e32 v82, v70
	s_waitcnt lgkmcnt(0)
	v_pk_add_f32 v[72:73], v[72:73], v[74:75]
	ds_bpermute_b32 v74, v152, v72
	ds_bpermute_b32 v75, v152, v73
	v_mul_f32_e32 v85, v71, v71
	v_mov_b32_e32 v84, v71
	s_waitcnt lgkmcnt(0)
	v_pk_add_f32 v[72:73], v[72:73], v[74:75]
	ds_bpermute_b32 v74, v153, v72
	ds_bpermute_b32 v75, v153, v73
	s_waitcnt lgkmcnt(0)
	v_pk_add_f32 v[72:73], v[72:73], v[74:75]
	v_add_f32_e32 v74, 0, v89
	v_mul_f32_e32 v75, v89, v89
	v_pk_add_f32 v[74:75], v[74:75], v[76:77]
	s_nop 0
	v_pk_add_f32 v[74:75], v[74:75], v[78:79]
	v_mul_f32_e32 v79, v94, v94
	v_pk_add_f32 v[74:75], v[74:75], v[80:81]
	ds_bpermute_b32 v76, v150, v74
	ds_bpermute_b32 v77, v150, v75
	v_mov_b32_e32 v78, v94
	v_mul_f32_e32 v81, v102, v102
	v_mov_b32_e32 v80, v102
	s_waitcnt lgkmcnt(0)
	v_pk_add_f32 v[74:75], v[74:75], v[76:77]
	ds_bpermute_b32 v76, v151, v74
	ds_bpermute_b32 v77, v151, v75
	s_waitcnt lgkmcnt(0)
	v_pk_add_f32 v[74:75], v[74:75], v[76:77]
	ds_bpermute_b32 v76, v152, v74
	ds_bpermute_b32 v77, v152, v75
	s_waitcnt lgkmcnt(0)
	v_pk_add_f32 v[74:75], v[74:75], v[76:77]
	ds_bpermute_b32 v76, v153, v74
	ds_bpermute_b32 v77, v153, v75
	s_waitcnt lgkmcnt(0)
	v_pk_add_f32 v[74:75], v[74:75], v[76:77]
	v_add_f32_e32 v76, 0, v90
	v_mul_f32_e32 v77, v90, v90
	v_pk_add_f32 v[76:77], v[76:77], v[78:79]
	s_nop 0
	v_pk_add_f32 v[76:77], v[76:77], v[80:81]
	v_mul_f32_e32 v81, v95, v95
	v_pk_add_f32 v[76:77], v[76:77], v[82:83]
	ds_bpermute_b32 v78, v150, v76
	ds_bpermute_b32 v79, v150, v77
	v_mov_b32_e32 v80, v95
	v_mul_f32_e32 v83, v103, v103
	v_mov_b32_e32 v82, v103
	s_waitcnt lgkmcnt(0)
	v_pk_add_f32 v[76:77], v[76:77], v[78:79]
	ds_bpermute_b32 v78, v151, v76
	ds_bpermute_b32 v79, v151, v77
	s_waitcnt lgkmcnt(0)
	v_pk_add_f32 v[76:77], v[76:77], v[78:79]
	ds_bpermute_b32 v78, v152, v76
	ds_bpermute_b32 v79, v152, v77
	s_waitcnt lgkmcnt(0)
	v_pk_add_f32 v[76:77], v[76:77], v[78:79]
	ds_bpermute_b32 v78, v153, v76
	ds_bpermute_b32 v79, v153, v77
	s_waitcnt lgkmcnt(0)
	v_pk_add_f32 v[76:77], v[76:77], v[78:79]
	v_add_f32_e32 v78, 0, v91
	v_mul_f32_e32 v79, v91, v91
	v_pk_add_f32 v[78:79], v[78:79], v[80:81]
	s_nop 0
	v_pk_add_f32 v[78:79], v[78:79], v[82:83]
	s_nop 0
	v_pk_add_f32 v[78:79], v[78:79], v[84:85]
	ds_bpermute_b32 v80, v150, v78
	ds_bpermute_b32 v81, v150, v79
	s_waitcnt lgkmcnt(0)
	v_pk_add_f32 v[78:79], v[78:79], v[80:81]
	ds_bpermute_b32 v80, v151, v78
	ds_bpermute_b32 v81, v151, v79
	s_waitcnt lgkmcnt(0)
	v_pk_add_f32 v[78:79], v[78:79], v[80:81]
	ds_bpermute_b32 v80, v152, v78
	ds_bpermute_b32 v81, v152, v79
	s_waitcnt lgkmcnt(0)
	v_pk_add_f32 v[78:79], v[78:79], v[80:81]
	ds_bpermute_b32 v80, v153, v78
	ds_bpermute_b32 v81, v153, v79
	s_waitcnt lgkmcnt(0)
	v_pk_add_f32 v[78:79], v[78:79], v[80:81]
	s_and_saveexec_b64 s[20:21], s[42:43]
	s_cbranch_execz .LBB0_414
	ds_write_b128 v170, v[72:75]
	ds_write_b128 v170, v[76:79] offset:16
